# KIND2 tile loop: LDS-DMA issue with scalar-side addressing (unit K/V bases in SGPR pairs, M0 by SALU) instead of 64-bit vector adds and readfirstlane per piece
# baseline (speedup 1.0000x reference)
; DI int crow(int reg, int h) { return (reg & 3) + 8 * (reg >> 2) + 4 * h; }
; template <int KIND>
; DI void attn_unit(const Params& p, int l, int b, int head, int qt, int qcol, int kcol, int vfeat, int gcol, int mixcol,
;                   int t1, int n1, int t2, int n2, char* smem) {
;     ...
;     if (KIND == 2) {
;         nrow = 2 * qt + (wave >> 1); r0w = min(max(nrow - 4, 0), 24);
;         qc = 32 * (wave & 1) + r; c0 = min(max(qc - 8, 0), 48);
;         float* bias = (float*)(smem + ATT_BIAS);
;         for (int i = tid; i < 15 * 32; i += NTHREADS) { const int rr = i >> 5, cc = i & 31; bias[i] = cc < 31 ? p.rpb[((size_t)l * 6 + head) * 465 + rr * 31 + cc] * LOG2E : -INFINITY; }
;     }
;     int bcol[2][16];
;     if (KIND == 2) {
; #pragma unroll
;         for (int t = 0; t < 2; ++t)
; #pragma unroll
;             for (int e = 0; e < 16; ++e) {
;                 const int kc = 32 * t + crow(e, h);
;                 bcol[t][e] = ((unsigned)(kc - c0) < 16u) ? (kc - qc + 15) * 4 : 31 * 4;
;             }
;     }
;     f32x16 O0[2], O1[2];
; #pragma unroll
;     for (int t = 0; t < 2; ++t)
; #pragma unroll
;         for (int e = 0; e < 16; ++e) { O0[t][e] = 0.f; O1[t][e] = 0.f; }
;     float l0 = 0.f, l1 = 0.f;
;     const float zb = p.lam[8 + l * 4 + ((KIND == 1 && qcol >= 2048) ? 3 : KIND)];
;     f32x16 cz;
; #pragma unroll
;     for (int e = 0; e < 16; ++e) cz[e] = -zb;
;     const int kvoff = (8 * wave + (lane >> 3)) * 64 + (((lane & 7) ^ (((wave & 1) << 2) | (lane >> 4))) << 3);
;     const int xr = (r >> 1) & 7;
.LBB0_121:
	s_cmp_lt_i32 s43, -3
	v_lshlrev_b32_e32 v164, 2, v2
	s_cbranch_scc1 .LBB0_106
	v_lshl_or_b32 v6, v7, 5, v3
	v_sub_u32_e64 v7, v6, 8 clamp
	v_min_u32_e32 v7, 48, v7
	s_mov_b64 s[62:63], s[6:7]
	s_mov_b64 s[98:99], s[4:5]
	v_mov_b32_e32 v160, v0
	v_add_u32_e32 v161, 0x1000, v0
	v_readfirstlane_b32 s101, v165
	v_sub_u32_e32 v0, v164, v7
	v_sub_u32_e32 v1, v164, v6
	v_lshl_add_u32 v1, v1, 2, 60
	v_cmp_gt_u32_e32 vcc, 16, v0
	v_or_b32_e32 v0, 1, v164
	s_waitcnt vmcnt(0)
	v_xor_b32_e32 v32, 0x80000000, v5
	v_cndmask_b32_e32 v166, v204, v1, vcc
	v_sub_u32_e32 v1, v0, v7
	v_sub_u32_e32 v0, v0, v6
	v_lshl_add_u32 v0, v0, 2, 60
	v_cmp_gt_u32_e32 vcc, 16, v1
	v_mov_b32_e32 v179, 0
	s_mov_b32 s46, 2
	v_cndmask_b32_e32 v167, v204, v0, vcc
	v_or_b32_e32 v0, 2, v164
	v_sub_u32_e32 v1, v0, v7
	v_sub_u32_e32 v0, v0, v6
	v_lshl_add_u32 v0, v0, 2, 60
	v_cmp_gt_u32_e32 vcc, 16, v1
	v_mov_b32_e32 v33, v32
	v_mov_b32_e32 v34, v32
	v_cndmask_b32_e32 v168, v204, v0, vcc
	v_or_b32_e32 v0, 3, v164
	v_sub_u32_e32 v1, v0, v7
	v_sub_u32_e32 v0, v0, v6
	v_lshl_add_u32 v0, v0, 2, 60
	v_cmp_gt_u32_e32 vcc, 16, v1
	v_mov_b32_e32 v35, v32
	v_mov_b32_e32 v36, v32
	v_cndmask_b32_e32 v169, v204, v0, vcc
	v_or_b32_e32 v0, 8, v164
	v_sub_u32_e32 v1, v0, v7
	v_sub_u32_e32 v0, v0, v6
	v_lshl_add_u32 v0, v0, 2, 60
	v_cmp_gt_u32_e32 vcc, 16, v1
	v_mov_b32_e32 v37, v32
	v_mov_b32_e32 v38, v32
	v_cndmask_b32_e32 v170, v204, v0, vcc
	v_or_b32_e32 v0, 9, v164
	v_sub_u32_e32 v1, v0, v7
	v_sub_u32_e32 v0, v0, v6
	v_lshl_add_u32 v0, v0, 2, 60
	v_cmp_gt_u32_e32 vcc, 16, v1
	v_mov_b32_e32 v39, v32
	v_mov_b32_e32 v40, v32
	v_cndmask_b32_e32 v171, v204, v0, vcc
	v_or_b32_e32 v0, 10, v164
	v_sub_u32_e32 v1, v0, v7
	v_sub_u32_e32 v0, v0, v6
	v_lshl_add_u32 v0, v0, 2, 60
	v_cmp_gt_u32_e32 vcc, 16, v1
	v_mov_b32_e32 v41, v32
	v_mov_b32_e32 v42, v32
	v_cndmask_b32_e32 v172, v204, v0, vcc
	v_or_b32_e32 v0, 11, v164
	v_sub_u32_e32 v1, v0, v7
	v_sub_u32_e32 v0, v0, v6
	v_lshl_add_u32 v0, v0, 2, 60
	v_cmp_gt_u32_e32 vcc, 16, v1
	v_mov_b32_e32 v43, v32
	v_mov_b32_e32 v44, v32
	v_cndmask_b32_e32 v173, v204, v0, vcc
	v_or_b32_e32 v0, 16, v164
	v_sub_u32_e32 v1, v0, v7
	v_sub_u32_e32 v0, v0, v6
	v_lshl_add_u32 v0, v0, 2, 60
	v_cmp_gt_u32_e32 vcc, 16, v1
	v_mov_b32_e32 v45, v32
	v_mov_b32_e32 v46, v32
	v_cndmask_b32_e32 v174, v204, v0, vcc
	v_or_b32_e32 v0, 17, v164
	v_sub_u32_e32 v1, v0, v7
	v_sub_u32_e32 v0, v0, v6
	v_lshl_add_u32 v0, v0, 2, 60
	v_cmp_gt_u32_e32 vcc, 16, v1
	v_mov_b32_e32 v47, v32
	s_add_i32 s47, s43, 4
	v_cndmask_b32_e32 v175, v204, v0, vcc
	v_or_b32_e32 v0, 18, v164
	v_sub_u32_e32 v1, v0, v7
	v_sub_u32_e32 v0, v0, v6
	v_lshl_add_u32 v0, v0, 2, 60
	v_cmp_gt_u32_e32 vcc, 16, v1
	v_lshlrev_b32_e32 v217, 7, v3
	s_sub_i32 s50, s42, s8
	v_cndmask_b32_e32 v176, v204, v0, vcc
	v_or_b32_e32 v0, 19, v164
	v_sub_u32_e32 v1, v0, v7
	v_sub_u32_e32 v0, v0, v6
	v_lshl_add_u32 v0, v0, 2, 60
	v_cmp_gt_u32_e32 vcc, 16, v1
	s_mov_b32 s51, 0
	s_mov_b32 s53, 0
	v_cndmask_b32_e32 v177, v204, v0, vcc
	v_or_b32_e32 v0, 24, v164
	v_sub_u32_e32 v1, v0, v7
	v_sub_u32_e32 v0, v0, v6
	v_lshl_add_u32 v0, v0, 2, 60
	v_cmp_gt_u32_e32 vcc, 16, v1
	v_mov_b32_e32 v3, v179
	v_mov_b32_e32 v5, v179
	v_cndmask_b32_e32 v178, v204, v0, vcc
	v_or_b32_e32 v0, 25, v164
	v_sub_u32_e32 v1, v0, v7
	v_sub_u32_e32 v0, v0, v6
	v_lshl_add_u32 v0, v0, 2, 60
	v_cmp_gt_u32_e32 vcc, 16, v1
	v_mov_b32_e32 v8, v179
	v_mov_b32_e32 v9, v179
	v_cndmask_b32_e32 v180, v204, v0, vcc
	v_or_b32_e32 v0, 26, v164
	v_sub_u32_e32 v1, v0, v7
	v_sub_u32_e32 v0, v0, v6
	v_lshl_add_u32 v0, v0, 2, 60
	v_cmp_gt_u32_e32 vcc, 16, v1
	v_mov_b32_e32 v10, v179
	v_mov_b32_e32 v11, v179
	v_cndmask_b32_e32 v181, v204, v0, vcc
	v_or_b32_e32 v0, 27, v164
	v_sub_u32_e32 v1, v0, v7
	v_sub_u32_e32 v0, v0, v6
	v_lshl_add_u32 v0, v0, 2, 60
	v_cmp_gt_u32_e32 vcc, 16, v1
	v_mov_b32_e32 v12, v179
	v_mov_b32_e32 v13, v179
	v_cndmask_b32_e32 v182, v204, v0, vcc
	v_or_b32_e32 v0, 32, v164
	v_sub_u32_e32 v1, v0, v7
	v_sub_u32_e32 v0, v0, v6
	v_lshl_add_u32 v0, v0, 2, 60
; DI int crow(int reg, int h) { return (reg & 3) + 8 * (reg >> 2) + 4 * h; }
; #define KV_ISSUE(tile_, slot_) do { \
;     const bf16_t* kp_ = kbase + (size_t)(tile_) * 4096 + kvoff; const bf16_t* vp_ = vbase + (size_t)(tile_) * 4096 + kvoff; \
;     char* lp_ = smem + (slot_) * ATT_SLOT + tid * 16; \
;     dma16(kp_, lp_); dma16(kp_ + 2048, lp_ + 4096); dma16(vp_, lp_ + ATT_V); dma16(vp_ + 2048, lp_ + ATT_V + 4096); } while (0)
; template <int KIND>
; DI void attn_unit(const Params& p, int l, int b, int head, int qt, int qcol, int kcol, int vfeat, int gcol, int mixcol,
;                   int t1, int n1, int t2, int n2, char* smem) {
;     ...
;     if (KIND == 2) {
;         nrow = 2 * qt + (wave >> 1); r0w = min(max(nrow - 4, 0), 24);
;         qc = 32 * (wave & 1) + r; c0 = min(max(qc - 8, 0), 48);
;         float* bias = (float*)(smem + ATT_BIAS);
;         for (int i = tid; i < 15 * 32; i += NTHREADS) { const int rr = i >> 5, cc = i & 31; bias[i] = cc < 31 ? p.rpb[((size_t)l * 6 + head) * 465 + rr * 31 + cc] * LOG2E : -INFINITY; }
;     }
;     int bcol[2][16];
;     if (KIND == 2) {
; #pragma unroll
;         for (int t = 0; t < 2; ++t)
; #pragma unroll
;             for (int e = 0; e < 16; ++e) {
;                 const int kc = 32 * t + crow(e, h);
;                 bcol[t][e] = ((unsigned)(kc - c0) < 16u) ? (kc - qc + 15) * 4 : 31 * 4;
;             }
;     }
;     f32x16 O0[2], O1[2];
; #pragma unroll
;     for (int t = 0; t < 2; ++t)
; #pragma unroll
;         for (int e = 0; e < 16; ++e) { O0[t][e] = 0.f; O1[t][e] = 0.f; }
;     float l0 = 0.f, l1 = 0.f;
;     const float zb = p.lam[8 + l * 4 + ((KIND == 1 && qcol >= 2048) ? 3 : KIND)];
;     f32x16 cz;
; #pragma unroll
;     for (int e = 0; e < 16; ++e) cz[e] = -zb;
;     const int kvoff = (8 * wave + (lane >> 3)) * 64 + (((lane & 7) ^ (((wave & 1) << 2) | (lane >> 4))) << 3);
;     const int xr = (r >> 1) & 7;
;     __syncthreads();
;     KV_ISSUE(t1, 0);
;     if (nt > 1) KV_ISSUE((1 < n1) ? t1 + 1 : t2 + (1 - n1), 1);
;     int sc = 0, sn = 2;
	v_cmp_gt_u32_e32 vcc, 16, v1
	v_mov_b32_e32 v14, v179
	v_mov_b32_e32 v15, v179
	v_cndmask_b32_e32 v183, v204, v0, vcc
	v_or_b32_e32 v0, 33, v164
	v_sub_u32_e32 v1, v0, v7
	v_sub_u32_e32 v0, v0, v6
	v_lshl_add_u32 v0, v0, 2, 60
	v_cmp_gt_u32_e32 vcc, 16, v1
	v_mov_b32_e32 v16, 0
	v_mov_b32_e32 v17, v179
	v_cndmask_b32_e32 v184, v204, v0, vcc
	v_or_b32_e32 v0, 34, v164
	v_sub_u32_e32 v1, v0, v7
	v_sub_u32_e32 v0, v0, v6
	v_lshl_add_u32 v0, v0, 2, 60
	v_cmp_gt_u32_e32 vcc, 16, v1
	v_mov_b32_e32 v18, v179
	v_mov_b32_e32 v19, v179
	v_cndmask_b32_e32 v185, v204, v0, vcc
	v_or_b32_e32 v0, 35, v164
	v_sub_u32_e32 v1, v0, v7
	v_sub_u32_e32 v0, v0, v6
	v_lshl_add_u32 v0, v0, 2, 60
	v_cmp_gt_u32_e32 vcc, 16, v1
	v_mov_b32_e32 v20, v179
	v_mov_b32_e32 v21, v179
	v_cndmask_b32_e32 v186, v204, v0, vcc
	v_or_b32_e32 v0, 40, v164
	v_sub_u32_e32 v1, v0, v7
	v_sub_u32_e32 v0, v0, v6
	v_lshl_add_u32 v0, v0, 2, 60
	v_cmp_gt_u32_e32 vcc, 16, v1
	v_mov_b32_e32 v22, v179
	v_mov_b32_e32 v23, v179
	v_cndmask_b32_e32 v187, v204, v0, vcc
	v_or_b32_e32 v0, 41, v164
	v_sub_u32_e32 v1, v0, v7
	v_sub_u32_e32 v0, v0, v6
	v_lshl_add_u32 v0, v0, 2, 60
	v_cmp_gt_u32_e32 vcc, 16, v1
	v_mov_b32_e32 v24, v179
	v_mov_b32_e32 v25, v179
	v_cndmask_b32_e32 v188, v204, v0, vcc
	v_or_b32_e32 v0, 42, v164
	v_sub_u32_e32 v1, v0, v7
	v_sub_u32_e32 v0, v0, v6
	v_lshl_add_u32 v0, v0, 2, 60
	v_cmp_gt_u32_e32 vcc, 16, v1
	v_mov_b32_e32 v26, v179
	v_mov_b32_e32 v27, v179
	v_cndmask_b32_e32 v189, v204, v0, vcc
	v_or_b32_e32 v0, 43, v164
	v_sub_u32_e32 v1, v0, v7
	v_sub_u32_e32 v0, v0, v6
	v_lshl_add_u32 v0, v0, 2, 60
	v_cmp_gt_u32_e32 vcc, 16, v1
	v_mov_b32_e32 v28, v179
	v_mov_b32_e32 v29, v179
	v_cndmask_b32_e32 v190, v204, v0, vcc
	v_or_b32_e32 v0, 48, v164
	v_sub_u32_e32 v1, v0, v7
	v_sub_u32_e32 v0, v0, v6
	v_lshl_add_u32 v0, v0, 2, 60
	v_cmp_gt_u32_e32 vcc, 16, v1
	v_mov_b32_e32 v30, v179
	v_mov_b32_e32 v31, v179
	v_cndmask_b32_e32 v191, v204, v0, vcc
	v_or_b32_e32 v0, 49, v164
	v_sub_u32_e32 v1, v0, v7
	v_sub_u32_e32 v0, v0, v6
	v_lshl_add_u32 v0, v0, 2, 60
	v_cmp_gt_u32_e32 vcc, 16, v1
	s_nop 1
	v_cndmask_b32_e32 v192, v204, v0, vcc
	v_or_b32_e32 v0, 50, v164
	v_sub_u32_e32 v1, v0, v7
	v_sub_u32_e32 v0, v0, v6
	v_lshl_add_u32 v0, v0, 2, 60
	v_cmp_gt_u32_e32 vcc, 16, v1
	s_nop 1
	v_cndmask_b32_e32 v194, v204, v0, vcc
	v_or_b32_e32 v0, 51, v164
	v_sub_u32_e32 v1, v0, v7
	v_sub_u32_e32 v0, v0, v6
	v_lshl_add_u32 v0, v0, 2, 60
	v_cmp_gt_u32_e32 vcc, 16, v1
	s_nop 1
	v_cndmask_b32_e32 v195, v204, v0, vcc
	v_or_b32_e32 v0, 56, v164
	v_sub_u32_e32 v1, v0, v7
	v_sub_u32_e32 v0, v0, v6
	v_lshl_add_u32 v0, v0, 2, 60
	v_cmp_gt_u32_e32 vcc, 16, v1
	s_nop 1
	v_cndmask_b32_e32 v196, v204, v0, vcc
	v_or_b32_e32 v0, 57, v164
	v_sub_u32_e32 v1, v0, v7
	v_sub_u32_e32 v0, v0, v6
	v_lshl_add_u32 v0, v0, 2, 60
	v_cmp_gt_u32_e32 vcc, 16, v1
	s_nop 1
	v_cndmask_b32_e32 v197, v204, v0, vcc
	v_or_b32_e32 v0, 58, v164
	v_sub_u32_e32 v1, v0, v7
	v_sub_u32_e32 v0, v0, v6
	v_lshl_add_u32 v0, v0, 2, 60
	v_cmp_gt_u32_e32 vcc, 16, v1
	s_nop 1
	v_cndmask_b32_e32 v198, v204, v0, vcc
	v_or_b32_e32 v0, 59, v164
	v_sub_u32_e32 v1, v0, v7
	v_sub_u32_e32 v0, v0, v6
	v_lshl_add_u32 v0, v0, 2, 60
	v_cmp_gt_u32_e32 vcc, 16, v1
	v_bfe_u32 v1, v4, 1, 3
	v_mov_b32_e32 v6, v179
	v_cndmask_b32_e32 v199, v204, v0, vcc
	v_lshrrev_b32_e32 v0, 1, v4
	v_ashrrev_i32_e32 v4, 7, v4
	v_add_u32_e32 v214, s9, v4
	v_bitop3_b32 v0, v2, v0, 7 bitop3:0x78
	v_max_i32_e32 v4, 4, v214
	v_lshlrev_b32_e32 v218, 4, v0
	v_bitop3_b32 v0, v2, v1, 2 bitop3:0x36
	v_add_u32_e32 v4, -4, v4
	v_lshlrev_b32_e32 v219, 4, v0
	v_bitop3_b32 v0, v2, v1, 4 bitop3:0x36
	v_min_u32_e32 v215, 24, v4
	v_lshlrev_b32_e32 v220, 4, v0
	v_bitop3_b32 v0, v2, v1, 6 bitop3:0x36
	v_add_u32_e32 v216, 8, v215
	v_lshlrev_b32_e32 v221, 4, v0
	v_mov_b32_e32 v0, 0
	v_mov_b32_e32 v1, v179
	v_mov_b32_e32 v2, v179
	v_mov_b32_e32 v4, v179
	v_mov_b32_e32 v7, v179
	s_add_i32 s52, s53, 1
	s_cmp_ge_i32 s52, s47
	s_mov_b64 s[4:5], -1
	s_cbranch_scc0 .LBB0_125
	s_branch .LBB0_124

; #define KV_ISSUE(tile_, slot_) do { \
;     const bf16_t* kp_ = kbase + (size_t)(tile_) * 4096 + kvoff; const bf16_t* vp_ = vbase + (size_t)(tile_) * 4096 + kvoff; \
;     char* lp_ = smem + (slot_) * ATT_SLOT + tid * 16; \
;     dma16(kp_, lp_); dma16(kp_ + 2048, lp_ + 4096); dma16(vp_, lp_ + ATT_V); dma16(vp_ + 2048, lp_ + ATT_V + 4096); } while (0)
; template <int KIND>
; DI void attn_unit(const Params& p, int l, int b, int head, int qt, int qcol, int kcol, int vfeat, int gcol, int mixcol,
;                   int t1, int n1, int t2, int n2, char* smem) {
;     ...
;         if (it + 2 < nt) { const int nx = (it + 2 < n1) ? t1 + it + 2 : t2 + (it + 2 - n1); KV_ISSUE(nx, sn); }
;         sc = (sc == 2) ? 0 : sc + 1; sn = (sn == 2) ? 0 : sn + 1;
.LBB0_129:
	s_or_b64 exec, exec, s[4:5]
	s_add_i32 s4, s53, 2
	s_cmp_ge_i32 s4, s47
	s_cbranch_scc1 .LBB0_131
	s_add_i32 s57, s57, 2
	s_add_i32 s58, s58, 26
	s_cmp_lt_i32 s4, s43
	s_cselect_b32 s4, s57, s58
	s_ashr_i32 s5, s4, 31
	s_lshl_b64 s[4:5], s[4:5], 13
	s_add_u32 s40, s62, s4
	s_addc_u32 s41, s63, s5
	s_add_u32 s4, s98, s4
	s_addc_u32 s5, s99, s5
	s_lshl_b32 m0, s46, 14
	s_add_u32 m0, m0, s101
	s_nop 0
	global_load_lds_dwordx4 v160, s[40:41]
	s_add_u32 m0, m0, 0x1000
	s_nop 0
	global_load_lds_dwordx4 v161, s[40:41]
	s_add_u32 m0, m0, 0x1000
	s_nop 0
	global_load_lds_dwordx4 v160, s[4:5]
	s_add_u32 m0, m0, 0x1000
	s_nop 0
	global_load_lds_dwordx4 v161, s[4:5]
